# K loop of the multi-tile GEMM phases (FFN1 up, in-proj, FFN2 up): the first K iteration of a workgroup's 2nd+ tile skips its first two vmcnt(8) waits (all prefetched LDS-DMA loads already landed at th
# speedup vs baseline: 1.0039x; 1.0039x over previous
; #define PG8_STAGE(bufoff, gbase, voff) do { _Pragma("unroll") for (int _i = 0; _i < 2; ++_i) \
;         __builtin_amdgcn_global_load_lds((const unsigned*)((const char*)(gbase) + (voff)[_i]), (PG8_LAS unsigned*)(lds + (bufoff) + ldsw + _i * 8192), 16, 0, 0); } while (0)
; #define PG8_LDA(dst, b, h) do { _Pragma("unroll") for (int m = 0; m < 4; ++m) _Pragma("unroll") for (int k = 0; k < 2; ++k) dst[m][k] = *(const PG8_LAS bf16x8*)(lds + PG8_SA(b, h) + aoff + m * 2048 + k * 1024); } while (0)
; #define PG8_LDB(dst, b, h) do { _Pragma("unroll") for (int n = 0; n < 2; ++n) _Pragma("unroll") for (int k = 0; k < 2; ++k) dst[n][k] = *(const PG8_LAS bf16x8*)(lds + PG8_SB(b, h) + boff + n * 2048 + k * 1024); } while (0)
; #define PG8_MMA(ai, bj, At, Bt) do { __builtin_amdgcn_s_setprio(1); _Pragma("unroll") for (int m = 0; m < 4; ++m) _Pragma("unroll") for (int n = 0; n < 2; ++n) _Pragma("unroll") for (int k = 0; k < 2; ++k) \
;         acc[ai][bj][m][n] = __builtin_amdgcn_mfma_f32_16x16x32_bf16(Bt[n][k], At[m][k], acc[ai][bj][m][n], 0, 0, 0); __builtin_amdgcn_s_setprio(0); } while (0)
; #define PG8_WAIT_V(n) asm volatile("s_waitcnt vmcnt(" #n ")" ::: "memory")
; #define PG8_WAIT_L(n) asm volatile("s_waitcnt lgkmcnt(" #n ")" ::: "memory")
; #define PG8_BAR __builtin_amdgcn_s_barrier()
; #define PG8_SCHED __builtin_amdgcn_sched_barrier(0)
; template <class Epi, class Sched, bool ALIGN_EPI = false, bool SP2 = false>
; __device__ __forceinline__ void gemm_phase(PG8_LAS unsigned char* lds, const Gemm g, const Sched& S, const Epi& E) {
;     ...
;         for (int t = 0; t < nt; t += 2) {
;             const bool last = (t == nt - 2);
;             const char* a1 = cA + (size_t)(t + 1) * kstep;
;             const char* a2 = last ? nA : cA + (size_t)(t + 2) * kstep; const char* b2 = last ? nB : cB + (size_t)(t + 2) * kstep;
;             const char* a3 = a2 + kstep; const char* b3 = b2 + kstep;
;             if (last && has_next) S.a_ready(nxt);
;             if constexpr (SP2) {
;             PG8_LDB(B0, 0, 0); PG8_LDB(B1, 0, 1); PG8_SCHED; PG8_LDA(At, 0, 0); PG8_STAGE(PG8_SA(1, 1), a1 + hstep, voffA);
;             PG8_WAIT_V(8); PG8_WAIT_L(0); PG8_BAR; PG8_MMA(0, 0, At, B0); PG8_MMA(0, 1, At, B1); PG8_BAR; PG8_SCHED;
;             PG8_LDA(At, 0, 1); PG8_STAGE(PG8_SB(0, 0), b2, voffB); PG8_STAGE(PG8_SB(0, 1), b2 + hstep, voffB); PG8_STAGE(PG8_SA(0, 0), a2, voffA);
.LBB0_3165:
	s_add_i32 s61, s34, 2
	s_add_u32 s62, s30, 0x80
	s_addc_u32 s35, s31, 0
	s_add_i32 s64, 0, 0x10000
	s_cmp_eq_u32 s53, s34
	s_cselect_b32 s35, s1, s35
	s_cselect_b32 s34, s0, s62
	v_add_u32_e32 v148, s64, v151
	s_cselect_b32 s63, s29, s60
	s_cselect_b32 s62, s28, s59
	s_add_i32 s65, 0, 0x14000
	ds_read_b128 v[130:133], v148
	ds_read_b128 v[156:159], v148 offset:1024
	ds_read_b128 v[162:165], v148 offset:2048
	ds_read_b128 v[166:169], v148 offset:3072
	v_add_u32_e32 v148, s65, v151
	ds_read_b128 v[170:173], v148
	ds_read_b128 v[174:177], v148 offset:1024
	ds_read_b128 v[178:181], v148 offset:2048
	ds_read_b128 v[182:185], v148 offset:3072
	v_lshl_add_u64 v[148:149], s[30:31], 0, v[146:147]
	s_add_i32 m0, s46, 0xc000
	ds_read_b128 v[186:189], v161
	ds_read_b128 v[190:193], v161 offset:1024
	ds_read_b128 v[194:197], v161 offset:2048
	ds_read_b128 v[198:201], v161 offset:3072
	ds_read_b128 v[202:205], v161 offset:4096
	ds_read_b128 v[206:209], v161 offset:5120
	ds_read_b128 v[210:213], v161 offset:6144
	ds_read_b128 v[214:217], v161 offset:7168
	global_load_lds_dwordx4 v[148:149], off
	v_lshl_add_u64 v[148:149], s[30:31], 0, v[144:145]
	s_add_i32 m0, s46, 0xe000
	s_nop 0
	global_load_lds_dwordx4 v[148:149], off
	s_cmp_eq_u32 s61, 2
	s_cbranch_scc1 .Lmy_kf0a
.Lmy_kw0a:
	s_waitcnt vmcnt(8)
.Lmy_kc0a:
	s_waitcnt lgkmcnt(0)
	s_barrier
	s_setprio 1
	s_waitcnt lgkmcnt(0)
	v_mfma_f32_16x16x32_bf16 v[122:125], v[130:133], v[186:189], v[122:125]
	v_mfma_f32_16x16x32_bf16 v[126:129], v[162:165], v[186:189], v[126:129]
	v_mfma_f32_16x16x32_bf16 v[110:113], v[130:133], v[194:197], v[110:113]
	v_mfma_f32_16x16x32_bf16 v[106:109], v[162:165], v[194:197], v[106:109]
	v_mfma_f32_16x16x32_bf16 v[94:97], v[130:133], v[202:205], v[94:97]
	v_mfma_f32_16x16x32_bf16 v[90:93], v[162:165], v[202:205], v[90:93]
	v_mfma_f32_16x16x32_bf16 v[78:81], v[130:133], v[210:213], v[78:81]
	v_mfma_f32_16x16x32_bf16 v[74:77], v[162:165], v[210:213], v[74:77]
	v_mfma_f32_16x16x32_bf16 v[122:125], v[156:159], v[190:193], v[122:125]
	v_mfma_f32_16x16x32_bf16 v[126:129], v[166:169], v[190:193], v[126:129]
	v_mfma_f32_16x16x32_bf16 v[110:113], v[156:159], v[198:201], v[110:113]
	v_mfma_f32_16x16x32_bf16 v[106:109], v[166:169], v[198:201], v[106:109]
	v_mfma_f32_16x16x32_bf16 v[94:97], v[156:159], v[206:209], v[94:97]
	v_mfma_f32_16x16x32_bf16 v[90:93], v[166:169], v[206:209], v[90:93]
	v_mfma_f32_16x16x32_bf16 v[78:81], v[156:159], v[214:217], v[78:81]
	v_mfma_f32_16x16x32_bf16 v[74:77], v[166:169], v[214:217], v[74:77]
	s_setprio 0
	s_setprio 1
	v_mfma_f32_16x16x32_bf16 v[118:121], v[170:173], v[186:189], v[118:121]
	v_mfma_f32_16x16x32_bf16 v[114:117], v[178:181], v[186:189], v[114:117]
	v_mfma_f32_16x16x32_bf16 v[102:105], v[170:173], v[194:197], v[102:105]
	v_mfma_f32_16x16x32_bf16 v[98:101], v[178:181], v[194:197], v[98:101]
	v_mfma_f32_16x16x32_bf16 v[86:89], v[170:173], v[202:205], v[86:89]
	v_mfma_f32_16x16x32_bf16 v[82:85], v[178:181], v[202:205], v[82:85]
	v_mfma_f32_16x16x32_bf16 v[70:73], v[170:173], v[210:213], v[70:73]
	v_mfma_f32_16x16x32_bf16 v[66:69], v[178:181], v[210:213], v[66:69]
	v_mfma_f32_16x16x32_bf16 v[118:121], v[174:177], v[190:193], v[118:121]
	v_mfma_f32_16x16x32_bf16 v[114:117], v[182:185], v[190:193], v[114:117]
	v_mfma_f32_16x16x32_bf16 v[102:105], v[174:177], v[198:201], v[102:105]
	v_mfma_f32_16x16x32_bf16 v[98:101], v[182:185], v[198:201], v[98:101]
	v_mfma_f32_16x16x32_bf16 v[86:89], v[174:177], v[206:209], v[86:89]
	v_mfma_f32_16x16x32_bf16 v[82:85], v[182:185], v[206:209], v[82:85]
	v_mfma_f32_16x16x32_bf16 v[70:73], v[174:177], v[214:217], v[70:73]
	v_mfma_f32_16x16x32_bf16 v[66:69], v[182:185], v[214:217], v[66:69]
	s_setprio 0
	s_barrier
	s_add_i32 s64, s64, s41
	v_lshl_add_u64 v[148:149], s[62:63], 0, v[136:137]
	s_mov_b32 m0, s64
	ds_read_b128 v[186:189], v161 offset:16384
	ds_read_b128 v[190:193], v161 offset:17408
	ds_read_b128 v[194:197], v161 offset:18432
	ds_read_b128 v[198:201], v161 offset:19456
	ds_read_b128 v[202:205], v161 offset:20480
	ds_read_b128 v[206:209], v161 offset:21504
	ds_read_b128 v[210:213], v161 offset:22528
	ds_read_b128 v[214:217], v161 offset:23552
	global_load_lds_dwordx4 v[148:149], off
	s_add_i32 m0, s64, 0x2000
	v_lshl_add_u64 v[152:153], s[62:63], 0, v[140:141]
	s_add_u32 s62, s62, s16
	s_addc_u32 s63, s63, s17
	s_add_i32 s64, s65, s41
	global_load_lds_dwordx4 v[152:153], off
	v_lshl_add_u64 v[218:219], s[62:63], 0, v[136:137]
	s_mov_b32 m0, s64
	v_lshl_add_u64 v[242:243], s[62:63], 0, v[140:141]
	global_load_lds_dwordx4 v[218:219], off
	s_add_i32 m0, s64, 0x2000
	v_lshl_add_u64 v[244:245], s[34:35], 0, v[134:135]
	global_load_lds_dwordx4 v[242:243], off
	s_mov_b32 m0, s46
	v_lshl_add_u64 v[246:247], s[34:35], 0, v[138:139]
	global_load_lds_dwordx4 v[244:245], off
	s_mov_b32 m0, s47
	s_nop 0
	global_load_lds_dwordx4 v[246:247], off
	s_cmp_eq_u32 s61, 2
	s_cbranch_scc1 .Lmy_kf0b

; #define PG8_STAGE(bufoff, gbase, voff) do { _Pragma("unroll") for (int _i = 0; _i < 2; ++_i) \
;         __builtin_amdgcn_global_load_lds((const unsigned*)((const char*)(gbase) + (voff)[_i]), (PG8_LAS unsigned*)(lds + (bufoff) + ldsw + _i * 8192), 16, 0, 0); } while (0)
; #define PG8_LDA(dst, b, h) do { _Pragma("unroll") for (int m = 0; m < 4; ++m) _Pragma("unroll") for (int k = 0; k < 2; ++k) dst[m][k] = *(const PG8_LAS bf16x8*)(lds + PG8_SA(b, h) + aoff + m * 2048 + k * 1024); } while (0)
; #define PG8_LDB(dst, b, h) do { _Pragma("unroll") for (int n = 0; n < 2; ++n) _Pragma("unroll") for (int k = 0; k < 2; ++k) dst[n][k] = *(const PG8_LAS bf16x8*)(lds + PG8_SB(b, h) + boff + n * 2048 + k * 1024); } while (0)
; #define PG8_MMA(ai, bj, At, Bt) do { __builtin_amdgcn_s_setprio(1); _Pragma("unroll") for (int m = 0; m < 4; ++m) _Pragma("unroll") for (int n = 0; n < 2; ++n) _Pragma("unroll") for (int k = 0; k < 2; ++k) \
;         acc[ai][bj][m][n] = __builtin_amdgcn_mfma_f32_16x16x32_bf16(Bt[n][k], At[m][k], acc[ai][bj][m][n], 0, 0, 0); __builtin_amdgcn_s_setprio(0); } while (0)
; #define PG8_WAIT_V(n) asm volatile("s_waitcnt vmcnt(" #n ")" ::: "memory")
; #define PG8_WAIT_L(n) asm volatile("s_waitcnt lgkmcnt(" #n ")" ::: "memory")
; #define PG8_BAR __builtin_amdgcn_s_barrier()
; #define PG8_SCHED __builtin_amdgcn_sched_barrier(0)
; template <class Epi, class Sched, bool ALIGN_EPI = false, bool SP2 = false>
; __device__ __forceinline__ void gemm_phase(PG8_LAS unsigned char* lds, const Gemm g, const Sched& S, const Epi& E) {
;     ...
;             PG8_WAIT_V(8); PG8_WAIT_L(0); PG8_BAR; PG8_MMA(1, 0, At, B0); PG8_MMA(1, 1, At, B1); PG8_BAR; PG8_SCHED;
;             PG8_LDB(B0, 1, 0); PG8_LDB(B1, 1, 1); PG8_SCHED; PG8_LDA(At, 1, 0); PG8_STAGE(PG8_SA(0, 1), a2 + hstep, voffA);
;             PG8_WAIT_V(8); PG8_WAIT_L(0); PG8_BAR; PG8_MMA(0, 0, At, B0); PG8_MMA(0, 1, At, B1); PG8_BAR; PG8_SCHED;
.Lmy_kc0b:
	s_waitcnt lgkmcnt(0)
	s_barrier
	s_setprio 1
	s_waitcnt lgkmcnt(0)
	v_mfma_f32_16x16x32_bf16 v[62:65], v[130:133], v[186:189], v[62:65]
	v_mfma_f32_16x16x32_bf16 v[58:61], v[162:165], v[186:189], v[58:61]
	v_mfma_f32_16x16x32_bf16 v[46:49], v[130:133], v[194:197], v[46:49]
	v_mfma_f32_16x16x32_bf16 v[42:45], v[162:165], v[194:197], v[42:45]
	v_mfma_f32_16x16x32_bf16 v[30:33], v[130:133], v[202:205], v[30:33]
	v_mfma_f32_16x16x32_bf16 v[26:29], v[162:165], v[202:205], v[26:29]
	v_mfma_f32_16x16x32_bf16 v[14:17], v[130:133], v[210:213], v[14:17]
	v_mfma_f32_16x16x32_bf16 v[10:13], v[162:165], v[210:213], v[10:13]
	v_mfma_f32_16x16x32_bf16 v[62:65], v[156:159], v[190:193], v[62:65]
	v_mfma_f32_16x16x32_bf16 v[58:61], v[166:169], v[190:193], v[58:61]
	v_mfma_f32_16x16x32_bf16 v[46:49], v[156:159], v[198:201], v[46:49]
	v_mfma_f32_16x16x32_bf16 v[42:45], v[166:169], v[198:201], v[42:45]
	v_mfma_f32_16x16x32_bf16 v[30:33], v[156:159], v[206:209], v[30:33]
	v_mfma_f32_16x16x32_bf16 v[26:29], v[166:169], v[206:209], v[26:29]
	v_mfma_f32_16x16x32_bf16 v[14:17], v[156:159], v[214:217], v[14:17]
	v_mfma_f32_16x16x32_bf16 v[10:13], v[166:169], v[214:217], v[10:13]
	s_setprio 0
	s_setprio 1
	v_mfma_f32_16x16x32_bf16 v[54:57], v[170:173], v[186:189], v[54:57]
	v_mfma_f32_16x16x32_bf16 v[50:53], v[178:181], v[186:189], v[50:53]
	v_mfma_f32_16x16x32_bf16 v[38:41], v[170:173], v[194:197], v[38:41]
	v_mfma_f32_16x16x32_bf16 v[34:37], v[178:181], v[194:197], v[34:37]
	v_mfma_f32_16x16x32_bf16 v[22:25], v[170:173], v[202:205], v[22:25]
	v_mfma_f32_16x16x32_bf16 v[18:21], v[178:181], v[202:205], v[18:21]
	v_mfma_f32_16x16x32_bf16 v[6:9], v[170:173], v[210:213], v[6:9]
	v_mfma_f32_16x16x32_bf16 v[2:5], v[178:181], v[210:213], v[2:5]
	v_mfma_f32_16x16x32_bf16 v[54:57], v[174:177], v[190:193], v[54:57]
	v_mfma_f32_16x16x32_bf16 v[50:53], v[182:185], v[190:193], v[50:53]
	v_mfma_f32_16x16x32_bf16 v[38:41], v[174:177], v[198:201], v[38:41]
	v_mfma_f32_16x16x32_bf16 v[34:37], v[182:185], v[198:201], v[34:37]
	v_mfma_f32_16x16x32_bf16 v[22:25], v[174:177], v[206:209], v[22:25]
	v_mfma_f32_16x16x32_bf16 v[18:21], v[182:185], v[206:209], v[18:21]
	v_mfma_f32_16x16x32_bf16 v[6:9], v[174:177], v[214:217], v[6:9]
	v_mfma_f32_16x16x32_bf16 v[2:5], v[182:185], v[214:217], v[2:5]
	s_setprio 0
	s_barrier
	s_add_i32 s62, 0, 0x18000
	v_add_u32_e32 v150, s62, v151
	s_add_i32 s63, 0, 0x1c000
	ds_read_b128 v[130:133], v150
	ds_read_b128 v[156:159], v150 offset:1024
	ds_read_b128 v[162:165], v150 offset:2048
	ds_read_b128 v[166:169], v150 offset:3072
	v_add_u32_e32 v150, s63, v151
	ds_read_b128 v[170:173], v150
	ds_read_b128 v[174:177], v150 offset:1024
	ds_read_b128 v[178:181], v150 offset:2048
	ds_read_b128 v[182:185], v150 offset:3072
	s_add_u32 s34, s34, s16
	s_addc_u32 s35, s35, s17
	s_mov_b32 m0, s48
	v_lshl_add_u64 v[248:249], s[34:35], 0, v[134:135]
	ds_read_b128 v[186:189], v161 offset:32768
	ds_read_b128 v[190:193], v161 offset:33792
	ds_read_b128 v[194:197], v161 offset:34816
	ds_read_b128 v[198:201], v161 offset:35840
	ds_read_b128 v[202:205], v161 offset:36864
	ds_read_b128 v[206:209], v161 offset:37888
	ds_read_b128 v[210:213], v161 offset:38912
	ds_read_b128 v[214:217], v161 offset:39936
	global_load_lds_dwordx4 v[248:249], off
	v_lshl_add_u64 v[248:249], s[34:35], 0, v[138:139]
	s_mov_b32 m0, s49
	s_nop 0
	global_load_lds_dwordx4 v[248:249], off
	s_waitcnt vmcnt(8)
	s_waitcnt lgkmcnt(0)
	s_barrier
	s_setprio 1
	s_waitcnt lgkmcnt(0)
	v_mfma_f32_16x16x32_bf16 v[122:125], v[130:133], v[186:189], v[122:125]
	v_mfma_f32_16x16x32_bf16 v[126:129], v[162:165], v[186:189], v[126:129]
	v_mfma_f32_16x16x32_bf16 v[110:113], v[130:133], v[194:197], v[110:113]
	v_mfma_f32_16x16x32_bf16 v[106:109], v[162:165], v[194:197], v[106:109]
	v_mfma_f32_16x16x32_bf16 v[94:97], v[130:133], v[202:205], v[94:97]
	v_mfma_f32_16x16x32_bf16 v[90:93], v[162:165], v[202:205], v[90:93]
	v_mfma_f32_16x16x32_bf16 v[78:81], v[130:133], v[210:213], v[78:81]
	v_mfma_f32_16x16x32_bf16 v[74:77], v[162:165], v[210:213], v[74:77]
	v_mfma_f32_16x16x32_bf16 v[122:125], v[156:159], v[190:193], v[122:125]
	v_mfma_f32_16x16x32_bf16 v[126:129], v[166:169], v[190:193], v[126:129]
	v_mfma_f32_16x16x32_bf16 v[110:113], v[156:159], v[198:201], v[110:113]
	v_mfma_f32_16x16x32_bf16 v[106:109], v[166:169], v[198:201], v[106:109]
	v_mfma_f32_16x16x32_bf16 v[94:97], v[156:159], v[206:209], v[94:97]
	v_mfma_f32_16x16x32_bf16 v[90:93], v[166:169], v[206:209], v[90:93]
	v_mfma_f32_16x16x32_bf16 v[78:81], v[156:159], v[214:217], v[78:81]
	v_mfma_f32_16x16x32_bf16 v[74:77], v[166:169], v[214:217], v[74:77]
	s_setprio 0
	s_setprio 1
	v_mfma_f32_16x16x32_bf16 v[118:121], v[170:173], v[186:189], v[118:121]
	v_mfma_f32_16x16x32_bf16 v[114:117], v[178:181], v[186:189], v[114:117]
	v_mfma_f32_16x16x32_bf16 v[102:105], v[170:173], v[194:197], v[102:105]
	v_mfma_f32_16x16x32_bf16 v[98:101], v[178:181], v[194:197], v[98:101]
	v_mfma_f32_16x16x32_bf16 v[86:89], v[170:173], v[202:205], v[86:89]
	v_mfma_f32_16x16x32_bf16 v[82:85], v[178:181], v[202:205], v[82:85]
	v_mfma_f32_16x16x32_bf16 v[70:73], v[170:173], v[210:213], v[70:73]
	v_mfma_f32_16x16x32_bf16 v[66:69], v[178:181], v[210:213], v[66:69]
	v_mfma_f32_16x16x32_bf16 v[118:121], v[174:177], v[190:193], v[118:121]
	v_mfma_f32_16x16x32_bf16 v[114:117], v[182:185], v[190:193], v[114:117]
	v_mfma_f32_16x16x32_bf16 v[102:105], v[174:177], v[198:201], v[102:105]
	v_mfma_f32_16x16x32_bf16 v[98:101], v[182:185], v[198:201], v[98:101]
	v_mfma_f32_16x16x32_bf16 v[86:89], v[174:177], v[206:209], v[86:89]
	v_mfma_f32_16x16x32_bf16 v[82:85], v[182:185], v[206:209], v[82:85]
	v_mfma_f32_16x16x32_bf16 v[70:73], v[174:177], v[214:217], v[70:73]
	v_mfma_f32_16x16x32_bf16 v[66:69], v[182:185], v[214:217], v[66:69]
	s_setprio 0
	s_barrier
; #define PG8_STAGE(bufoff, gbase, voff) do { _Pragma("unroll") for (int _i = 0; _i < 2; ++_i) \
;         __builtin_amdgcn_global_load_lds((const unsigned*)((const char*)(gbase) + (voff)[_i]), (PG8_LAS unsigned*)(lds + (bufoff) + ldsw + _i * 8192), 16, 0, 0); } while (0)
; #define PG8_LDA(dst, b, h) do { _Pragma("unroll") for (int m = 0; m < 4; ++m) _Pragma("unroll") for (int k = 0; k < 2; ++k) dst[m][k] = *(const PG8_LAS bf16x8*)(lds + PG8_SA(b, h) + aoff + m * 2048 + k * 1024); } while (0)
; #define PG8_MMA(ai, bj, At, Bt) do { __builtin_amdgcn_s_setprio(1); _Pragma("unroll") for (int m = 0; m < 4; ++m) _Pragma("unroll") for (int n = 0; n < 2; ++n) _Pragma("unroll") for (int k = 0; k < 2; ++k) \
;         acc[ai][bj][m][n] = __builtin_amdgcn_mfma_f32_16x16x32_bf16(Bt[n][k], At[m][k], acc[ai][bj][m][n], 0, 0, 0); __builtin_amdgcn_s_setprio(0); } while (0)
; #define PG8_WAIT_V(n) asm volatile("s_waitcnt vmcnt(" #n ")" ::: "memory")
; #define PG8_WAIT_L(n) asm volatile("s_waitcnt lgkmcnt(" #n ")" ::: "memory")
; #define PG8_BAR __builtin_amdgcn_s_barrier()
; #define PG8_SCHED __builtin_amdgcn_sched_barrier(0)
; template <class Epi, class Sched, bool ALIGN_EPI = false, bool SP2 = false>
; __device__ __forceinline__ void gemm_phase(PG8_LAS unsigned char* lds, const Gemm g, const Sched& S, const Epi& E) {
;     ...
;             PG8_WAIT_V(8); PG8_WAIT_L(0); PG8_BAR; PG8_MMA(0, 0, At, B0); PG8_MMA(0, 1, At, B1); PG8_BAR; PG8_SCHED;
;             PG8_LDA(At, 1, 1); PG8_STAGE(PG8_SB(1, 0), b3, voffB); PG8_STAGE(PG8_SB(1, 1), b3 + hstep, voffB); PG8_STAGE(PG8_SA(1, 0), a3, voffA);
;             PG8_WAIT_V(8); PG8_WAIT_L(0); PG8_BAR; PG8_MMA(1, 0, At, B0); PG8_MMA(1, 1, At, B1); PG8_BAR; PG8_SCHED;
	s_add_i32 s34, s62, s41
	v_lshl_add_u64 v[148:149], v[148:149], 0, s[92:93]
	s_mov_b32 m0, s34
	ds_read_b128 v[186:189], v161 offset:49152
	ds_read_b128 v[190:193], v161 offset:50176
	ds_read_b128 v[194:197], v161 offset:51200
	ds_read_b128 v[198:201], v161 offset:52224
	ds_read_b128 v[202:205], v161 offset:53248
	ds_read_b128 v[206:209], v161 offset:54272
	ds_read_b128 v[210:213], v161 offset:55296
	ds_read_b128 v[214:217], v161 offset:56320
	global_load_lds_dwordx4 v[148:149], off
	v_lshl_add_u64 v[148:149], v[152:153], 0, s[92:93]
	s_add_i32 m0, s34, 0x2000
	s_add_i32 s34, s63, s41
	global_load_lds_dwordx4 v[148:149], off
	v_lshl_add_u64 v[148:149], v[218:219], 0, s[92:93]
	s_mov_b32 m0, s34
	s_nop 0
	global_load_lds_dwordx4 v[148:149], off
	v_lshl_add_u64 v[148:149], v[242:243], 0, s[92:93]
	s_add_i32 m0, s34, 0x2000
	s_nop 0
	global_load_lds_dwordx4 v[148:149], off
	v_lshl_add_u64 v[148:149], v[244:245], 0, s[92:93]
	s_mov_b32 m0, s50
	s_nop 0
	global_load_lds_dwordx4 v[148:149], off
	v_lshl_add_u64 v[148:149], v[246:247], 0, s[92:93]
	s_mov_b32 m0, s51
	s_nop 0
	global_load_lds_dwordx4 v[148:149], off
	s_waitcnt vmcnt(8)
	s_waitcnt lgkmcnt(0)
	s_barrier
	s_setprio 1
	s_waitcnt lgkmcnt(0)
	v_mfma_f32_16x16x32_bf16 v[62:65], v[130:133], v[186:189], v[62:65]
	v_mfma_f32_16x16x32_bf16 v[58:61], v[162:165], v[186:189], v[58:61]
	v_mfma_f32_16x16x32_bf16 v[46:49], v[130:133], v[194:197], v[46:49]
	v_mfma_f32_16x16x32_bf16 v[42:45], v[162:165], v[194:197], v[42:45]
	v_mfma_f32_16x16x32_bf16 v[30:33], v[130:133], v[202:205], v[30:33]
	v_mfma_f32_16x16x32_bf16 v[26:29], v[162:165], v[202:205], v[26:29]
	v_mfma_f32_16x16x32_bf16 v[14:17], v[130:133], v[210:213], v[14:17]
	v_mfma_f32_16x16x32_bf16 v[10:13], v[162:165], v[210:213], v[10:13]
	v_mfma_f32_16x16x32_bf16 v[62:65], v[156:159], v[190:193], v[62:65]
	v_mfma_f32_16x16x32_bf16 v[58:61], v[166:169], v[190:193], v[58:61]
	v_mfma_f32_16x16x32_bf16 v[46:49], v[156:159], v[198:201], v[46:49]
	v_mfma_f32_16x16x32_bf16 v[42:45], v[166:169], v[198:201], v[42:45]
	v_mfma_f32_16x16x32_bf16 v[30:33], v[156:159], v[206:209], v[30:33]
	v_mfma_f32_16x16x32_bf16 v[26:29], v[166:169], v[206:209], v[26:29]
	v_mfma_f32_16x16x32_bf16 v[14:17], v[156:159], v[214:217], v[14:17]
	v_mfma_f32_16x16x32_bf16 v[10:13], v[166:169], v[214:217], v[10:13]
	s_setprio 0
	s_setprio 1
	v_mfma_f32_16x16x32_bf16 v[54:57], v[170:173], v[186:189], v[54:57]
	v_mfma_f32_16x16x32_bf16 v[50:53], v[178:181], v[186:189], v[50:53]
	v_mfma_f32_16x16x32_bf16 v[38:41], v[170:173], v[194:197], v[38:41]
	v_mfma_f32_16x16x32_bf16 v[34:37], v[178:181], v[194:197], v[34:37]
	v_mfma_f32_16x16x32_bf16 v[22:25], v[170:173], v[202:205], v[22:25]
	v_mfma_f32_16x16x32_bf16 v[18:21], v[178:181], v[202:205], v[18:21]
	v_mfma_f32_16x16x32_bf16 v[6:9], v[170:173], v[210:213], v[6:9]
	v_mfma_f32_16x16x32_bf16 v[2:5], v[178:181], v[210:213], v[2:5]
	v_mfma_f32_16x16x32_bf16 v[54:57], v[174:177], v[190:193], v[54:57]
	v_mfma_f32_16x16x32_bf16 v[50:53], v[182:185], v[190:193], v[50:53]
	v_mfma_f32_16x16x32_bf16 v[38:41], v[174:177], v[198:201], v[38:41]
	v_mfma_f32_16x16x32_bf16 v[34:37], v[182:185], v[198:201], v[34:37]
	v_mfma_f32_16x16x32_bf16 v[22:25], v[174:177], v[206:209], v[22:25]
	v_mfma_f32_16x16x32_bf16 v[18:21], v[182:185], v[206:209], v[18:21]
	v_mfma_f32_16x16x32_bf16 v[6:9], v[174:177], v[214:217], v[6:9]
	v_mfma_f32_16x16x32_bf16 v[2:5], v[182:185], v[214:217], v[2:5]
	s_setprio 0
	s_barrier
	s_add_u32 s59, s59, 0x100
	s_addc_u32 s60, s60, 0
	s_add_u32 s30, s30, 0x100
	s_addc_u32 s31, s31, 0
	s_cmp_ge_i32 s61, s52
	s_mov_b32 s34, s61
	s_cbranch_scc0 .LBB0_3165

; #define PG8_MMA(ai, bj, At, Bt) do { __builtin_amdgcn_s_setprio(1); _Pragma("unroll") for (int m = 0; m < 4; ++m) _Pragma("unroll") for (int n = 0; n < 2; ++n) _Pragma("unroll") for (int k = 0; k < 2; ++k) \
;         acc[ai][bj][m][n] = __builtin_amdgcn_mfma_f32_16x16x32_bf16(Bt[n][k], At[m][k], acc[ai][bj][m][n], 0, 0, 0); __builtin_amdgcn_s_setprio(0); } while (0)
; #define PG8_WAIT_V(n) asm volatile("s_waitcnt vmcnt(" #n ")" ::: "memory")
; #define PG8_WAIT_L(n) asm volatile("s_waitcnt lgkmcnt(" #n ")" ::: "memory")
; #define PG8_BAR __builtin_amdgcn_s_barrier()
; #define PG8_SCHED __builtin_amdgcn_sched_barrier(0)
; template <class Epi, class Sched, bool ALIGN_EPI = false, bool SP2 = false>
; __device__ __forceinline__ void gemm_phase(PG8_LAS unsigned char* lds, const Gemm g, const Sched& S, const Epi& E) {
;     ...
;             PG8_WAIT_V(8); PG8_WAIT_L(0); PG8_BAR; PG8_MMA(0, 0, At, B0); PG8_MMA(0, 1, At, B1); PG8_BAR; PG8_SCHED;
.Lmy_kf0a:
	s_cmp_gt_u32 s54, 1
	s_cbranch_scc1 .Lmy_kc0a
	s_branch .Lmy_kw0a

; #define PG8_STAGE(bufoff, gbase, voff) do { _Pragma("unroll") for (int _i = 0; _i < 2; ++_i) \
;         __builtin_amdgcn_global_load_lds((const unsigned*)((const char*)(gbase) + (voff)[_i]), (PG8_LAS unsigned*)(lds + (bufoff) + ldsw + _i * 8192), 16, 0, 0); } while (0)
; #define PG8_LDA(dst, b, h) do { _Pragma("unroll") for (int m = 0; m < 4; ++m) _Pragma("unroll") for (int k = 0; k < 2; ++k) dst[m][k] = *(const PG8_LAS bf16x8*)(lds + PG8_SA(b, h) + aoff + m * 2048 + k * 1024); } while (0)
; #define PG8_LDB(dst, b, h) do { _Pragma("unroll") for (int n = 0; n < 2; ++n) _Pragma("unroll") for (int k = 0; k < 2; ++k) dst[n][k] = *(const PG8_LAS bf16x8*)(lds + PG8_SB(b, h) + boff + n * 2048 + k * 1024); } while (0)
; #define PG8_SCHED __builtin_amdgcn_sched_barrier(0)
; template <class Epi, class Sched, bool ALIGN_EPI = false, bool SP2 = false>
; __device__ __forceinline__ void gemm_phase(PG8_LAS unsigned char* lds, const Gemm g, const Sched& S, const Epi& E) {
;     ...
;         for (int t = 0; t < nt; t += 2) {
;             const bool last = (t == nt - 2);
;             const char* a1 = cA + (size_t)(t + 1) * kstep;
;             const char* a2 = last ? nA : cA + (size_t)(t + 2) * kstep; const char* b2 = last ? nB : cB + (size_t)(t + 2) * kstep;
;             const char* a3 = a2 + kstep; const char* b3 = b2 + kstep;
;             if (last && has_next) S.a_ready(nxt);
;             if constexpr (SP2) {
;             PG8_LDB(B0, 0, 0); PG8_LDB(B1, 0, 1); PG8_SCHED; PG8_LDA(At, 0, 0); PG8_STAGE(PG8_SA(1, 1), a1 + hstep, voffA);
.LBB0_3346:
	s_add_i32 s58, s28, 2
	s_add_u32 s59, s26, 0x80
	s_addc_u32 s29, s27, 0
	s_add_i32 s62, 0, 0x10000
	s_cmp_eq_u32 s50, s28
	s_cselect_b32 s29, s1, s29
	s_cselect_b32 s28, s0, s59
	v_add_u32_e32 v148, s62, v149
	s_cselect_b32 s61, s25, s57
	s_cselect_b32 s60, s24, s56
	s_add_i32 s59, 0, 0x14000
	ds_read_b128 v[130:133], v148
	ds_read_b128 v[154:157], v148 offset:1024
	ds_read_b128 v[158:161], v148 offset:2048
	ds_read_b128 v[162:165], v148 offset:3072
	v_add_u32_e32 v148, s59, v149
	ds_read_b128 v[166:169], v148
	ds_read_b128 v[170:173], v148 offset:1024
	ds_read_b128 v[174:177], v148 offset:2048
	ds_read_b128 v[178:181], v148 offset:3072
	v_lshl_add_u64 v[214:215], s[26:27], 0, v[146:147]
	s_add_i32 m0, s43, 0xc000
	ds_read_b128 v[182:185], v153
	ds_read_b128 v[186:189], v153 offset:1024
	ds_read_b128 v[190:193], v153 offset:2048
	ds_read_b128 v[194:197], v153 offset:3072
	ds_read_b128 v[198:201], v153 offset:4096
	ds_read_b128 v[202:205], v153 offset:5120
	ds_read_b128 v[206:209], v153 offset:6144
	ds_read_b128 v[210:213], v153 offset:7168
	global_load_lds_dwordx4 v[214:215], off
	v_lshl_add_u64 v[214:215], s[26:27], 0, v[144:145]
	s_add_i32 m0, s43, 0xe000
	s_nop 0
	global_load_lds_dwordx4 v[214:215], off
	s_cmp_eq_u32 s58, 2
	s_cbranch_scc1 .Lmy_kf1a

; #define PG8_STAGE(bufoff, gbase, voff) do { _Pragma("unroll") for (int _i = 0; _i < 2; ++_i) \
;         __builtin_amdgcn_global_load_lds((const unsigned*)((const char*)(gbase) + (voff)[_i]), (PG8_LAS unsigned*)(lds + (bufoff) + ldsw + _i * 8192), 16, 0, 0); } while (0)
; #define PG8_LDA(dst, b, h) do { _Pragma("unroll") for (int m = 0; m < 4; ++m) _Pragma("unroll") for (int k = 0; k < 2; ++k) dst[m][k] = *(const PG8_LAS bf16x8*)(lds + PG8_SA(b, h) + aoff + m * 2048 + k * 1024); } while (0)
; #define PG8_MMA(ai, bj, At, Bt) do { __builtin_amdgcn_s_setprio(1); _Pragma("unroll") for (int m = 0; m < 4; ++m) _Pragma("unroll") for (int n = 0; n < 2; ++n) _Pragma("unroll") for (int k = 0; k < 2; ++k) \
;         acc[ai][bj][m][n] = __builtin_amdgcn_mfma_f32_16x16x32_bf16(Bt[n][k], At[m][k], acc[ai][bj][m][n], 0, 0, 0); __builtin_amdgcn_s_setprio(0); } while (0)
; #define PG8_WAIT_V(n) asm volatile("s_waitcnt vmcnt(" #n ")" ::: "memory")
; #define PG8_WAIT_L(n) asm volatile("s_waitcnt lgkmcnt(" #n ")" ::: "memory")
; #define PG8_BAR __builtin_amdgcn_s_barrier()
; #define PG8_SCHED __builtin_amdgcn_sched_barrier(0)
; template <class Epi, class Sched, bool ALIGN_EPI = false, bool SP2 = false>
; __device__ __forceinline__ void gemm_phase(PG8_LAS unsigned char* lds, const Gemm g, const Sched& S, const Epi& E) {
;     ...
;             PG8_WAIT_V(8); PG8_WAIT_L(0); PG8_BAR; PG8_MMA(0, 0, At, B0); PG8_MMA(0, 1, At, B1); PG8_BAR; PG8_SCHED;
;             PG8_LDA(At, 0, 1); PG8_STAGE(PG8_SB(0, 0), b2, voffB); PG8_STAGE(PG8_SB(0, 1), b2 + hstep, voffB); PG8_STAGE(PG8_SA(0, 0), a2, voffA);
.Lmy_kc1a:
	s_waitcnt lgkmcnt(0)
	s_barrier
	s_setprio 1
	s_waitcnt lgkmcnt(0)
	v_mfma_f32_16x16x32_bf16 v[126:129], v[130:133], v[182:185], v[126:129]
	v_mfma_f32_16x16x32_bf16 v[122:125], v[158:161], v[182:185], v[122:125]
	v_mfma_f32_16x16x32_bf16 v[110:113], v[130:133], v[190:193], v[110:113]
	v_mfma_f32_16x16x32_bf16 v[106:109], v[158:161], v[190:193], v[106:109]
	v_mfma_f32_16x16x32_bf16 v[94:97], v[130:133], v[198:201], v[94:97]
	v_mfma_f32_16x16x32_bf16 v[90:93], v[158:161], v[198:201], v[90:93]
	v_mfma_f32_16x16x32_bf16 v[78:81], v[130:133], v[206:209], v[78:81]
	v_mfma_f32_16x16x32_bf16 v[74:77], v[158:161], v[206:209], v[74:77]
	v_mfma_f32_16x16x32_bf16 v[126:129], v[154:157], v[186:189], v[126:129]
	v_mfma_f32_16x16x32_bf16 v[122:125], v[162:165], v[186:189], v[122:125]
	v_mfma_f32_16x16x32_bf16 v[110:113], v[154:157], v[194:197], v[110:113]
	v_mfma_f32_16x16x32_bf16 v[106:109], v[162:165], v[194:197], v[106:109]
	v_mfma_f32_16x16x32_bf16 v[94:97], v[154:157], v[202:205], v[94:97]
	v_mfma_f32_16x16x32_bf16 v[90:93], v[162:165], v[202:205], v[90:93]
	v_mfma_f32_16x16x32_bf16 v[78:81], v[154:157], v[210:213], v[78:81]
	v_mfma_f32_16x16x32_bf16 v[74:77], v[162:165], v[210:213], v[74:77]
	s_setprio 0
	s_setprio 1
	v_mfma_f32_16x16x32_bf16 v[118:121], v[166:169], v[182:185], v[118:121]
	v_mfma_f32_16x16x32_bf16 v[114:117], v[174:177], v[182:185], v[114:117]
	v_mfma_f32_16x16x32_bf16 v[102:105], v[166:169], v[190:193], v[102:105]
	v_mfma_f32_16x16x32_bf16 v[98:101], v[174:177], v[190:193], v[98:101]
	v_mfma_f32_16x16x32_bf16 v[86:89], v[166:169], v[198:201], v[86:89]
	v_mfma_f32_16x16x32_bf16 v[82:85], v[174:177], v[198:201], v[82:85]
	v_mfma_f32_16x16x32_bf16 v[70:73], v[166:169], v[206:209], v[70:73]
	v_mfma_f32_16x16x32_bf16 v[66:69], v[174:177], v[206:209], v[66:69]
	v_mfma_f32_16x16x32_bf16 v[118:121], v[170:173], v[186:189], v[118:121]
	v_mfma_f32_16x16x32_bf16 v[114:117], v[178:181], v[186:189], v[114:117]
	v_mfma_f32_16x16x32_bf16 v[102:105], v[170:173], v[194:197], v[102:105]
	v_mfma_f32_16x16x32_bf16 v[98:101], v[178:181], v[194:197], v[98:101]
	v_mfma_f32_16x16x32_bf16 v[86:89], v[170:173], v[202:205], v[86:89]
	v_mfma_f32_16x16x32_bf16 v[82:85], v[178:181], v[202:205], v[82:85]
	v_mfma_f32_16x16x32_bf16 v[70:73], v[170:173], v[210:213], v[70:73]
	v_mfma_f32_16x16x32_bf16 v[66:69], v[178:181], v[210:213], v[66:69]
	s_setprio 0
	s_barrier
	s_add_i32 s62, s62, s38
	v_lshl_add_u64 v[214:215], s[60:61], 0, v[136:137]
	s_mov_b32 m0, s62
	ds_read_b128 v[182:185], v153 offset:16384
	ds_read_b128 v[186:189], v153 offset:17408
	ds_read_b128 v[190:193], v153 offset:18432
	ds_read_b128 v[194:197], v153 offset:19456
	ds_read_b128 v[198:201], v153 offset:20480
	ds_read_b128 v[202:205], v153 offset:21504
	ds_read_b128 v[206:209], v153 offset:22528
	ds_read_b128 v[210:213], v153 offset:23552
	global_load_lds_dwordx4 v[214:215], off
	s_add_i32 m0, s62, 0x2000
	v_lshl_add_u64 v[216:217], s[60:61], 0, v[140:141]
	s_add_u32 s60, s60, s12
	s_addc_u32 s61, s61, s13
	s_add_i32 s59, s59, s38
	global_load_lds_dwordx4 v[216:217], off
	v_lshl_add_u64 v[218:219], s[60:61], 0, v[136:137]
	s_mov_b32 m0, s59
	v_lshl_add_u64 v[228:229], s[60:61], 0, v[140:141]
	global_load_lds_dwordx4 v[218:219], off
	s_add_i32 m0, s59, 0x2000
	v_lshl_add_u64 v[242:243], s[28:29], 0, v[134:135]
	global_load_lds_dwordx4 v[228:229], off
	s_mov_b32 m0, s43
	v_lshl_add_u64 v[244:245], s[28:29], 0, v[138:139]
	global_load_lds_dwordx4 v[242:243], off
	s_mov_b32 m0, s44
	s_nop 0
	global_load_lds_dwordx4 v[244:245], off
	s_cmp_eq_u32 s58, 2
	s_cbranch_scc1 .Lmy_kf1b

; #define PG8_STAGE(bufoff, gbase, voff) do { _Pragma("unroll") for (int _i = 0; _i < 2; ++_i) \
;         __builtin_amdgcn_global_load_lds((const unsigned*)((const char*)(gbase) + (voff)[_i]), (PG8_LAS unsigned*)(lds + (bufoff) + ldsw + _i * 8192), 16, 0, 0); } while (0)
; #define PG8_LDA(dst, b, h) do { _Pragma("unroll") for (int m = 0; m < 4; ++m) _Pragma("unroll") for (int k = 0; k < 2; ++k) dst[m][k] = *(const PG8_LAS bf16x8*)(lds + PG8_SA(b, h) + aoff + m * 2048 + k * 1024); } while (0)
; #define PG8_LDB(dst, b, h) do { _Pragma("unroll") for (int n = 0; n < 2; ++n) _Pragma("unroll") for (int k = 0; k < 2; ++k) dst[n][k] = *(const PG8_LAS bf16x8*)(lds + PG8_SB(b, h) + boff + n * 2048 + k * 1024); } while (0)
; #define PG8_MMA(ai, bj, At, Bt) do { __builtin_amdgcn_s_setprio(1); _Pragma("unroll") for (int m = 0; m < 4; ++m) _Pragma("unroll") for (int n = 0; n < 2; ++n) _Pragma("unroll") for (int k = 0; k < 2; ++k) \
;         acc[ai][bj][m][n] = __builtin_amdgcn_mfma_f32_16x16x32_bf16(Bt[n][k], At[m][k], acc[ai][bj][m][n], 0, 0, 0); __builtin_amdgcn_s_setprio(0); } while (0)
; #define PG8_WAIT_V(n) asm volatile("s_waitcnt vmcnt(" #n ")" ::: "memory")
; #define PG8_WAIT_L(n) asm volatile("s_waitcnt lgkmcnt(" #n ")" ::: "memory")
; #define PG8_BAR __builtin_amdgcn_s_barrier()
; #define PG8_SCHED __builtin_amdgcn_sched_barrier(0)
; template <class Epi, class Sched, bool ALIGN_EPI = false, bool SP2 = false>
; __device__ __forceinline__ void gemm_phase(PG8_LAS unsigned char* lds, const Gemm g, const Sched& S, const Epi& E) {
;     ...
;             PG8_WAIT_V(8); PG8_WAIT_L(0); PG8_BAR; PG8_MMA(1, 0, At, B0); PG8_MMA(1, 1, At, B1); PG8_BAR; PG8_SCHED;
;             PG8_LDB(B0, 1, 0); PG8_LDB(B1, 1, 1); PG8_SCHED; PG8_LDA(At, 1, 0); PG8_STAGE(PG8_SA(0, 1), a2 + hstep, voffA);
;             PG8_WAIT_V(8); PG8_WAIT_L(0); PG8_BAR; PG8_MMA(0, 0, At, B0); PG8_MMA(0, 1, At, B1); PG8_BAR; PG8_SCHED;
.Lmy_kc1b:
	s_waitcnt lgkmcnt(0)
	s_barrier
	s_setprio 1
	s_waitcnt lgkmcnt(0)
	v_mfma_f32_16x16x32_bf16 v[62:65], v[130:133], v[182:185], v[62:65]
	v_mfma_f32_16x16x32_bf16 v[58:61], v[158:161], v[182:185], v[58:61]
	v_mfma_f32_16x16x32_bf16 v[46:49], v[130:133], v[190:193], v[46:49]
	v_mfma_f32_16x16x32_bf16 v[42:45], v[158:161], v[190:193], v[42:45]
	v_mfma_f32_16x16x32_bf16 v[30:33], v[130:133], v[198:201], v[30:33]
	v_mfma_f32_16x16x32_bf16 v[26:29], v[158:161], v[198:201], v[26:29]
	v_mfma_f32_16x16x32_bf16 v[14:17], v[130:133], v[206:209], v[14:17]
	v_mfma_f32_16x16x32_bf16 v[10:13], v[158:161], v[206:209], v[10:13]
	v_mfma_f32_16x16x32_bf16 v[62:65], v[154:157], v[186:189], v[62:65]
	v_mfma_f32_16x16x32_bf16 v[58:61], v[162:165], v[186:189], v[58:61]
	v_mfma_f32_16x16x32_bf16 v[46:49], v[154:157], v[194:197], v[46:49]
	v_mfma_f32_16x16x32_bf16 v[42:45], v[162:165], v[194:197], v[42:45]
	v_mfma_f32_16x16x32_bf16 v[30:33], v[154:157], v[202:205], v[30:33]
	v_mfma_f32_16x16x32_bf16 v[26:29], v[162:165], v[202:205], v[26:29]
	v_mfma_f32_16x16x32_bf16 v[14:17], v[154:157], v[210:213], v[14:17]
	v_mfma_f32_16x16x32_bf16 v[10:13], v[162:165], v[210:213], v[10:13]
	s_setprio 0
	s_setprio 1
	v_mfma_f32_16x16x32_bf16 v[54:57], v[166:169], v[182:185], v[54:57]
	v_mfma_f32_16x16x32_bf16 v[50:53], v[174:177], v[182:185], v[50:53]
	v_mfma_f32_16x16x32_bf16 v[38:41], v[166:169], v[190:193], v[38:41]
	v_mfma_f32_16x16x32_bf16 v[34:37], v[174:177], v[190:193], v[34:37]
	v_mfma_f32_16x16x32_bf16 v[22:25], v[166:169], v[198:201], v[22:25]
	v_mfma_f32_16x16x32_bf16 v[18:21], v[174:177], v[198:201], v[18:21]
	v_mfma_f32_16x16x32_bf16 v[6:9], v[166:169], v[206:209], v[6:9]
	v_mfma_f32_16x16x32_bf16 v[2:5], v[174:177], v[206:209], v[2:5]
	v_mfma_f32_16x16x32_bf16 v[54:57], v[170:173], v[186:189], v[54:57]
	v_mfma_f32_16x16x32_bf16 v[50:53], v[178:181], v[186:189], v[50:53]
	v_mfma_f32_16x16x32_bf16 v[38:41], v[170:173], v[194:197], v[38:41]
	v_mfma_f32_16x16x32_bf16 v[34:37], v[178:181], v[194:197], v[34:37]
	v_mfma_f32_16x16x32_bf16 v[22:25], v[170:173], v[202:205], v[22:25]
	v_mfma_f32_16x16x32_bf16 v[18:21], v[178:181], v[202:205], v[18:21]
	v_mfma_f32_16x16x32_bf16 v[6:9], v[170:173], v[210:213], v[6:9]
	v_mfma_f32_16x16x32_bf16 v[2:5], v[178:181], v[210:213], v[2:5]
	s_setprio 0
	s_barrier
	s_add_i32 s59, 0, 0x18000
	v_add_u32_e32 v148, s59, v149
	s_add_i32 s60, 0, 0x1c000
	ds_read_b128 v[130:133], v148
	ds_read_b128 v[154:157], v148 offset:1024
	ds_read_b128 v[158:161], v148 offset:2048
	ds_read_b128 v[162:165], v148 offset:3072
	v_add_u32_e32 v148, s60, v149
	ds_read_b128 v[166:169], v148
	ds_read_b128 v[170:173], v148 offset:1024
	ds_read_b128 v[174:177], v148 offset:2048
	ds_read_b128 v[178:181], v148 offset:3072
	s_add_u32 s28, s28, s12
	s_addc_u32 s29, s29, s13
	s_mov_b32 m0, s45
	v_lshl_add_u64 v[246:247], s[28:29], 0, v[134:135]
	ds_read_b128 v[182:185], v153 offset:32768
	ds_read_b128 v[186:189], v153 offset:33792
	ds_read_b128 v[190:193], v153 offset:34816
	ds_read_b128 v[194:197], v153 offset:35840
	ds_read_b128 v[198:201], v153 offset:36864
	ds_read_b128 v[202:205], v153 offset:37888
	ds_read_b128 v[206:209], v153 offset:38912
	ds_read_b128 v[210:213], v153 offset:39936
	global_load_lds_dwordx4 v[246:247], off
	v_lshl_add_u64 v[246:247], s[28:29], 0, v[138:139]
	s_mov_b32 m0, s46
	s_nop 0
	global_load_lds_dwordx4 v[246:247], off
	s_waitcnt vmcnt(8)
	s_waitcnt lgkmcnt(0)
	s_barrier
	s_setprio 1
	s_waitcnt lgkmcnt(0)
	v_mfma_f32_16x16x32_bf16 v[126:129], v[130:133], v[182:185], v[126:129]
	v_mfma_f32_16x16x32_bf16 v[122:125], v[158:161], v[182:185], v[122:125]
	v_mfma_f32_16x16x32_bf16 v[110:113], v[130:133], v[190:193], v[110:113]
	v_mfma_f32_16x16x32_bf16 v[106:109], v[158:161], v[190:193], v[106:109]
	v_mfma_f32_16x16x32_bf16 v[94:97], v[130:133], v[198:201], v[94:97]
	v_mfma_f32_16x16x32_bf16 v[90:93], v[158:161], v[198:201], v[90:93]
	v_mfma_f32_16x16x32_bf16 v[78:81], v[130:133], v[206:209], v[78:81]
	v_mfma_f32_16x16x32_bf16 v[74:77], v[158:161], v[206:209], v[74:77]
	v_mfma_f32_16x16x32_bf16 v[126:129], v[154:157], v[186:189], v[126:129]
	v_mfma_f32_16x16x32_bf16 v[122:125], v[162:165], v[186:189], v[122:125]
	v_mfma_f32_16x16x32_bf16 v[110:113], v[154:157], v[194:197], v[110:113]
	v_mfma_f32_16x16x32_bf16 v[106:109], v[162:165], v[194:197], v[106:109]
	v_mfma_f32_16x16x32_bf16 v[94:97], v[154:157], v[202:205], v[94:97]
	v_mfma_f32_16x16x32_bf16 v[90:93], v[162:165], v[202:205], v[90:93]
	v_mfma_f32_16x16x32_bf16 v[78:81], v[154:157], v[210:213], v[78:81]
	v_mfma_f32_16x16x32_bf16 v[74:77], v[162:165], v[210:213], v[74:77]
	s_setprio 0
	s_setprio 1
	v_mfma_f32_16x16x32_bf16 v[118:121], v[166:169], v[182:185], v[118:121]
	v_mfma_f32_16x16x32_bf16 v[114:117], v[174:177], v[182:185], v[114:117]
	v_mfma_f32_16x16x32_bf16 v[102:105], v[166:169], v[190:193], v[102:105]
	v_mfma_f32_16x16x32_bf16 v[98:101], v[174:177], v[190:193], v[98:101]
	v_mfma_f32_16x16x32_bf16 v[86:89], v[166:169], v[198:201], v[86:89]
	v_mfma_f32_16x16x32_bf16 v[82:85], v[174:177], v[198:201], v[82:85]
	v_mfma_f32_16x16x32_bf16 v[70:73], v[166:169], v[206:209], v[70:73]
	v_mfma_f32_16x16x32_bf16 v[66:69], v[174:177], v[206:209], v[66:69]
	v_mfma_f32_16x16x32_bf16 v[118:121], v[170:173], v[186:189], v[118:121]
	v_mfma_f32_16x16x32_bf16 v[114:117], v[178:181], v[186:189], v[114:117]
	v_mfma_f32_16x16x32_bf16 v[102:105], v[170:173], v[194:197], v[102:105]
	v_mfma_f32_16x16x32_bf16 v[98:101], v[178:181], v[194:197], v[98:101]
	v_mfma_f32_16x16x32_bf16 v[86:89], v[170:173], v[202:205], v[86:89]
	v_mfma_f32_16x16x32_bf16 v[82:85], v[178:181], v[202:205], v[82:85]
	v_mfma_f32_16x16x32_bf16 v[70:73], v[170:173], v[210:213], v[70:73]
	v_mfma_f32_16x16x32_bf16 v[66:69], v[178:181], v[210:213], v[66:69]
	s_setprio 0
	s_barrier
; #define PG8_STAGE(bufoff, gbase, voff) do { _Pragma("unroll") for (int _i = 0; _i < 2; ++_i) \
;         __builtin_amdgcn_global_load_lds((const unsigned*)((const char*)(gbase) + (voff)[_i]), (PG8_LAS unsigned*)(lds + (bufoff) + ldsw + _i * 8192), 16, 0, 0); } while (0)
; #define PG8_LDA(dst, b, h) do { _Pragma("unroll") for (int m = 0; m < 4; ++m) _Pragma("unroll") for (int k = 0; k < 2; ++k) dst[m][k] = *(const PG8_LAS bf16x8*)(lds + PG8_SA(b, h) + aoff + m * 2048 + k * 1024); } while (0)
; #define PG8_MMA(ai, bj, At, Bt) do { __builtin_amdgcn_s_setprio(1); _Pragma("unroll") for (int m = 0; m < 4; ++m) _Pragma("unroll") for (int n = 0; n < 2; ++n) _Pragma("unroll") for (int k = 0; k < 2; ++k) \
;         acc[ai][bj][m][n] = __builtin_amdgcn_mfma_f32_16x16x32_bf16(Bt[n][k], At[m][k], acc[ai][bj][m][n], 0, 0, 0); __builtin_amdgcn_s_setprio(0); } while (0)
; #define PG8_WAIT_V(n) asm volatile("s_waitcnt vmcnt(" #n ")" ::: "memory")
; #define PG8_WAIT_L(n) asm volatile("s_waitcnt lgkmcnt(" #n ")" ::: "memory")
; #define PG8_BAR __builtin_amdgcn_s_barrier()
; #define PG8_SCHED __builtin_amdgcn_sched_barrier(0)
; template <class Epi, class Sched, bool ALIGN_EPI = false, bool SP2 = false>
; __device__ __forceinline__ void gemm_phase(PG8_LAS unsigned char* lds, const Gemm g, const Sched& S, const Epi& E) {
;     ...
;             PG8_WAIT_V(8); PG8_WAIT_L(0); PG8_BAR; PG8_MMA(0, 0, At, B0); PG8_MMA(0, 1, At, B1); PG8_BAR; PG8_SCHED;
;             PG8_LDA(At, 1, 1); PG8_STAGE(PG8_SB(1, 0), b3, voffB); PG8_STAGE(PG8_SB(1, 1), b3 + hstep, voffB); PG8_STAGE(PG8_SA(1, 0), a3, voffA);
;             PG8_WAIT_V(8); PG8_WAIT_L(0); PG8_BAR; PG8_MMA(1, 0, At, B0); PG8_MMA(1, 1, At, B1); PG8_BAR; PG8_SCHED;
	s_add_i32 s28, s59, s38
	v_lshl_add_u64 v[214:215], v[214:215], 0, s[92:93]
	s_mov_b32 m0, s28
	ds_read_b128 v[182:185], v153 offset:49152
	ds_read_b128 v[186:189], v153 offset:50176
	ds_read_b128 v[190:193], v153 offset:51200
	ds_read_b128 v[194:197], v153 offset:52224
	ds_read_b128 v[198:201], v153 offset:53248
	ds_read_b128 v[202:205], v153 offset:54272
	ds_read_b128 v[206:209], v153 offset:55296
	ds_read_b128 v[210:213], v153 offset:56320
	global_load_lds_dwordx4 v[214:215], off
	v_lshl_add_u64 v[214:215], v[216:217], 0, s[92:93]
	s_add_i32 m0, s28, 0x2000
	s_add_i32 s28, s60, s38
	global_load_lds_dwordx4 v[214:215], off
	v_lshl_add_u64 v[214:215], v[218:219], 0, s[92:93]
	s_mov_b32 m0, s28
	s_nop 0
	global_load_lds_dwordx4 v[214:215], off
	v_lshl_add_u64 v[214:215], v[228:229], 0, s[92:93]
	s_add_i32 m0, s28, 0x2000
	s_nop 0
	global_load_lds_dwordx4 v[214:215], off
	v_lshl_add_u64 v[214:215], v[242:243], 0, s[92:93]
	s_mov_b32 m0, s47
	s_nop 0
	global_load_lds_dwordx4 v[214:215], off
	v_lshl_add_u64 v[214:215], v[244:245], 0, s[92:93]
	s_mov_b32 m0, s48
	s_nop 0
	global_load_lds_dwordx4 v[214:215], off
	s_waitcnt vmcnt(8)
	s_waitcnt lgkmcnt(0)
	s_barrier
	s_setprio 1
	s_waitcnt lgkmcnt(0)
	v_mfma_f32_16x16x32_bf16 v[62:65], v[130:133], v[182:185], v[62:65]
	v_mfma_f32_16x16x32_bf16 v[58:61], v[158:161], v[182:185], v[58:61]
	v_mfma_f32_16x16x32_bf16 v[46:49], v[130:133], v[190:193], v[46:49]
	v_mfma_f32_16x16x32_bf16 v[42:45], v[158:161], v[190:193], v[42:45]
	v_mfma_f32_16x16x32_bf16 v[30:33], v[130:133], v[198:201], v[30:33]
	v_mfma_f32_16x16x32_bf16 v[26:29], v[158:161], v[198:201], v[26:29]
	v_mfma_f32_16x16x32_bf16 v[14:17], v[130:133], v[206:209], v[14:17]
	v_mfma_f32_16x16x32_bf16 v[10:13], v[158:161], v[206:209], v[10:13]
	v_mfma_f32_16x16x32_bf16 v[62:65], v[154:157], v[186:189], v[62:65]
	v_mfma_f32_16x16x32_bf16 v[58:61], v[162:165], v[186:189], v[58:61]
	v_mfma_f32_16x16x32_bf16 v[46:49], v[154:157], v[194:197], v[46:49]
	v_mfma_f32_16x16x32_bf16 v[42:45], v[162:165], v[194:197], v[42:45]
	v_mfma_f32_16x16x32_bf16 v[30:33], v[154:157], v[202:205], v[30:33]
	v_mfma_f32_16x16x32_bf16 v[26:29], v[162:165], v[202:205], v[26:29]
	v_mfma_f32_16x16x32_bf16 v[14:17], v[154:157], v[210:213], v[14:17]
	v_mfma_f32_16x16x32_bf16 v[10:13], v[162:165], v[210:213], v[10:13]
	s_setprio 0
	s_setprio 1
	v_mfma_f32_16x16x32_bf16 v[54:57], v[166:169], v[182:185], v[54:57]
	v_mfma_f32_16x16x32_bf16 v[50:53], v[174:177], v[182:185], v[50:53]
	v_mfma_f32_16x16x32_bf16 v[38:41], v[166:169], v[190:193], v[38:41]
	v_mfma_f32_16x16x32_bf16 v[34:37], v[174:177], v[190:193], v[34:37]
	v_mfma_f32_16x16x32_bf16 v[22:25], v[166:169], v[198:201], v[22:25]
	v_mfma_f32_16x16x32_bf16 v[18:21], v[174:177], v[198:201], v[18:21]
	v_mfma_f32_16x16x32_bf16 v[6:9], v[166:169], v[206:209], v[6:9]
	v_mfma_f32_16x16x32_bf16 v[2:5], v[174:177], v[206:209], v[2:5]
	v_mfma_f32_16x16x32_bf16 v[54:57], v[170:173], v[186:189], v[54:57]
	v_mfma_f32_16x16x32_bf16 v[50:53], v[178:181], v[186:189], v[50:53]
	v_mfma_f32_16x16x32_bf16 v[38:41], v[170:173], v[194:197], v[38:41]
	v_mfma_f32_16x16x32_bf16 v[34:37], v[178:181], v[194:197], v[34:37]
	v_mfma_f32_16x16x32_bf16 v[22:25], v[170:173], v[202:205], v[22:25]
	v_mfma_f32_16x16x32_bf16 v[18:21], v[178:181], v[202:205], v[18:21]
	v_mfma_f32_16x16x32_bf16 v[6:9], v[170:173], v[210:213], v[6:9]
	v_mfma_f32_16x16x32_bf16 v[2:5], v[178:181], v[210:213], v[2:5]
	s_setprio 0
	s_barrier
	s_add_u32 s56, s56, 0x100
	s_addc_u32 s57, s57, 0
	s_add_u32 s26, s26, 0x100
	s_addc_u32 s27, s27, 0
	s_cmp_ge_i32 s58, s49
	s_mov_b32 s28, s58
	s_cbranch_scc0 .LBB0_3346

; #define PG8_MMA(ai, bj, At, Bt) do { __builtin_amdgcn_s_setprio(1); _Pragma("unroll") for (int m = 0; m < 4; ++m) _Pragma("unroll") for (int n = 0; n < 2; ++n) _Pragma("unroll") for (int k = 0; k < 2; ++k) \
;         acc[ai][bj][m][n] = __builtin_amdgcn_mfma_f32_16x16x32_bf16(Bt[n][k], At[m][k], acc[ai][bj][m][n], 0, 0, 0); __builtin_amdgcn_s_setprio(0); } while (0)
; #define PG8_WAIT_V(n) asm volatile("s_waitcnt vmcnt(" #n ")" ::: "memory")
; #define PG8_WAIT_L(n) asm volatile("s_waitcnt lgkmcnt(" #n ")" ::: "memory")
; #define PG8_BAR __builtin_amdgcn_s_barrier()
; #define PG8_SCHED __builtin_amdgcn_sched_barrier(0)
; template <class Epi, class Sched, bool ALIGN_EPI = false, bool SP2 = false>
; __device__ __forceinline__ void gemm_phase(PG8_LAS unsigned char* lds, const Gemm g, const Sched& S, const Epi& E) {
;     ...
;             PG8_WAIT_V(8); PG8_WAIT_L(0); PG8_BAR; PG8_MMA(0, 0, At, B0); PG8_MMA(0, 1, At, B1); PG8_BAR; PG8_SCHED;
.Lmy_kf1a:
	s_cmp_gt_u32 s51, 1
	s_cbranch_scc1 .Lmy_kc1a
	s_branch .Lmy_kw1a

; #define PG8_STAGE(bufoff, gbase, voff) do { _Pragma("unroll") for (int _i = 0; _i < 2; ++_i) \
;         __builtin_amdgcn_global_load_lds((const unsigned*)((const char*)(gbase) + (voff)[_i]), (PG8_LAS unsigned*)(lds + (bufoff) + ldsw + _i * 8192), 16, 0, 0); } while (0)
; #define PG8_LDA(dst, b, h) do { _Pragma("unroll") for (int m = 0; m < 4; ++m) _Pragma("unroll") for (int k = 0; k < 2; ++k) dst[m][k] = *(const PG8_LAS bf16x8*)(lds + PG8_SA(b, h) + aoff + m * 2048 + k * 1024); } while (0)
; #define PG8_LDB(dst, b, h) do { _Pragma("unroll") for (int n = 0; n < 2; ++n) _Pragma("unroll") for (int k = 0; k < 2; ++k) dst[n][k] = *(const PG8_LAS bf16x8*)(lds + PG8_SB(b, h) + boff + n * 2048 + k * 1024); } while (0)
; #define PG8_SCHED __builtin_amdgcn_sched_barrier(0)
; template <class Epi, class Sched, bool ALIGN_EPI = false, bool SP2 = false>
; __device__ __forceinline__ void gemm_phase(PG8_LAS unsigned char* lds, const Gemm g, const Sched& S, const Epi& E) {
;     ...
;         for (int t = 0; t < nt; t += 2) {
;             const bool last = (t == nt - 2);
;             const char* a1 = cA + (size_t)(t + 1) * kstep;
;             const char* a2 = last ? nA : cA + (size_t)(t + 2) * kstep; const char* b2 = last ? nB : cB + (size_t)(t + 2) * kstep;
;             const char* a3 = a2 + kstep; const char* b3 = b2 + kstep;
;             if (last && has_next) S.a_ready(nxt);
;             if constexpr (SP2) {
;             PG8_LDB(B0, 0, 0); PG8_LDB(B1, 0, 1); PG8_SCHED; PG8_LDA(At, 0, 0); PG8_STAGE(PG8_SA(1, 1), a1 + hstep, voffA);
.LBB0_4845:
	s_add_i32 s55, s26, 2
	s_add_u32 s56, s24, 0x80
	s_addc_u32 s27, s25, 0
	s_add_i32 s58, 0, 0x10000
	s_cmp_eq_u32 s47, s26
	s_cselect_b32 s27, s1, s27
	s_cselect_b32 s26, s0, s56
	v_add_u32_e32 v148, s58, v151
	s_cselect_b32 s57, s23, s54
	s_cselect_b32 s56, s22, s53
	s_add_i32 s59, 0, 0x14000
	ds_read_b128 v[130:133], v148
	ds_read_b128 v[156:159], v148 offset:1024
	ds_read_b128 v[162:165], v148 offset:2048
	ds_read_b128 v[166:169], v148 offset:3072
	v_add_u32_e32 v148, s59, v151
	ds_read_b128 v[170:173], v148
	ds_read_b128 v[174:177], v148 offset:1024
	ds_read_b128 v[178:181], v148 offset:2048
	ds_read_b128 v[182:185], v148 offset:3072
	v_lshl_add_u64 v[148:149], s[24:25], 0, v[146:147]
	s_add_i32 m0, s40, 0xc000
	ds_read_b128 v[186:189], v161
	ds_read_b128 v[190:193], v161 offset:1024
	ds_read_b128 v[194:197], v161 offset:2048
	ds_read_b128 v[198:201], v161 offset:3072
	ds_read_b128 v[202:205], v161 offset:4096
	ds_read_b128 v[206:209], v161 offset:5120
	ds_read_b128 v[210:213], v161 offset:6144
	ds_read_b128 v[214:217], v161 offset:7168
	global_load_lds_dwordx4 v[148:149], off
	v_lshl_add_u64 v[148:149], s[24:25], 0, v[144:145]
	s_add_i32 m0, s40, 0xe000
	s_nop 0
	global_load_lds_dwordx4 v[148:149], off
	s_cmp_eq_u32 s55, 2
	s_cbranch_scc1 .Lmy_kf2a

; #define PG8_STAGE(bufoff, gbase, voff) do { _Pragma("unroll") for (int _i = 0; _i < 2; ++_i) \
;         __builtin_amdgcn_global_load_lds((const unsigned*)((const char*)(gbase) + (voff)[_i]), (PG8_LAS unsigned*)(lds + (bufoff) + ldsw + _i * 8192), 16, 0, 0); } while (0)
; #define PG8_LDA(dst, b, h) do { _Pragma("unroll") for (int m = 0; m < 4; ++m) _Pragma("unroll") for (int k = 0; k < 2; ++k) dst[m][k] = *(const PG8_LAS bf16x8*)(lds + PG8_SA(b, h) + aoff + m * 2048 + k * 1024); } while (0)
; #define PG8_MMA(ai, bj, At, Bt) do { __builtin_amdgcn_s_setprio(1); _Pragma("unroll") for (int m = 0; m < 4; ++m) _Pragma("unroll") for (int n = 0; n < 2; ++n) _Pragma("unroll") for (int k = 0; k < 2; ++k) \
;         acc[ai][bj][m][n] = __builtin_amdgcn_mfma_f32_16x16x32_bf16(Bt[n][k], At[m][k], acc[ai][bj][m][n], 0, 0, 0); __builtin_amdgcn_s_setprio(0); } while (0)
; #define PG8_WAIT_V(n) asm volatile("s_waitcnt vmcnt(" #n ")" ::: "memory")
; #define PG8_WAIT_L(n) asm volatile("s_waitcnt lgkmcnt(" #n ")" ::: "memory")
; #define PG8_BAR __builtin_amdgcn_s_barrier()
; #define PG8_SCHED __builtin_amdgcn_sched_barrier(0)
; template <class Epi, class Sched, bool ALIGN_EPI = false, bool SP2 = false>
; __device__ __forceinline__ void gemm_phase(PG8_LAS unsigned char* lds, const Gemm g, const Sched& S, const Epi& E) {
;     ...
;             PG8_WAIT_V(8); PG8_WAIT_L(0); PG8_BAR; PG8_MMA(0, 0, At, B0); PG8_MMA(0, 1, At, B1); PG8_BAR; PG8_SCHED;
;             PG8_LDA(At, 0, 1); PG8_STAGE(PG8_SB(0, 0), b2, voffB); PG8_STAGE(PG8_SB(0, 1), b2 + hstep, voffB); PG8_STAGE(PG8_SA(0, 0), a2, voffA);
.Lmy_kc2a:
	s_waitcnt lgkmcnt(0)
	s_barrier
	s_setprio 1
	s_waitcnt lgkmcnt(0)
	v_mfma_f32_16x16x32_bf16 v[122:125], v[130:133], v[186:189], v[122:125]
	v_mfma_f32_16x16x32_bf16 v[126:129], v[162:165], v[186:189], v[126:129]
	v_mfma_f32_16x16x32_bf16 v[110:113], v[130:133], v[194:197], v[110:113]
	v_mfma_f32_16x16x32_bf16 v[106:109], v[162:165], v[194:197], v[106:109]
	v_mfma_f32_16x16x32_bf16 v[94:97], v[130:133], v[202:205], v[94:97]
	v_mfma_f32_16x16x32_bf16 v[90:93], v[162:165], v[202:205], v[90:93]
	v_mfma_f32_16x16x32_bf16 v[78:81], v[130:133], v[210:213], v[78:81]
	v_mfma_f32_16x16x32_bf16 v[74:77], v[162:165], v[210:213], v[74:77]
	v_mfma_f32_16x16x32_bf16 v[122:125], v[156:159], v[190:193], v[122:125]
	v_mfma_f32_16x16x32_bf16 v[126:129], v[166:169], v[190:193], v[126:129]
	v_mfma_f32_16x16x32_bf16 v[110:113], v[156:159], v[198:201], v[110:113]
	v_mfma_f32_16x16x32_bf16 v[106:109], v[166:169], v[198:201], v[106:109]
	v_mfma_f32_16x16x32_bf16 v[94:97], v[156:159], v[206:209], v[94:97]
	v_mfma_f32_16x16x32_bf16 v[90:93], v[166:169], v[206:209], v[90:93]
	v_mfma_f32_16x16x32_bf16 v[78:81], v[156:159], v[214:217], v[78:81]
	v_mfma_f32_16x16x32_bf16 v[74:77], v[166:169], v[214:217], v[74:77]
	s_setprio 0
	s_setprio 1
	v_mfma_f32_16x16x32_bf16 v[118:121], v[170:173], v[186:189], v[118:121]
	v_mfma_f32_16x16x32_bf16 v[114:117], v[178:181], v[186:189], v[114:117]
	v_mfma_f32_16x16x32_bf16 v[102:105], v[170:173], v[194:197], v[102:105]
	v_mfma_f32_16x16x32_bf16 v[98:101], v[178:181], v[194:197], v[98:101]
	v_mfma_f32_16x16x32_bf16 v[86:89], v[170:173], v[202:205], v[86:89]
	v_mfma_f32_16x16x32_bf16 v[82:85], v[178:181], v[202:205], v[82:85]
	v_mfma_f32_16x16x32_bf16 v[70:73], v[170:173], v[210:213], v[70:73]
	v_mfma_f32_16x16x32_bf16 v[66:69], v[178:181], v[210:213], v[66:69]
	v_mfma_f32_16x16x32_bf16 v[118:121], v[174:177], v[190:193], v[118:121]
	v_mfma_f32_16x16x32_bf16 v[114:117], v[182:185], v[190:193], v[114:117]
	v_mfma_f32_16x16x32_bf16 v[102:105], v[174:177], v[198:201], v[102:105]
	v_mfma_f32_16x16x32_bf16 v[98:101], v[182:185], v[198:201], v[98:101]
	v_mfma_f32_16x16x32_bf16 v[86:89], v[174:177], v[206:209], v[86:89]
	v_mfma_f32_16x16x32_bf16 v[82:85], v[182:185], v[206:209], v[82:85]
	v_mfma_f32_16x16x32_bf16 v[70:73], v[174:177], v[214:217], v[70:73]
	v_mfma_f32_16x16x32_bf16 v[66:69], v[182:185], v[214:217], v[66:69]
	s_setprio 0
	s_barrier
	s_add_i32 s58, s58, s35
	v_lshl_add_u64 v[148:149], s[56:57], 0, v[136:137]
	s_mov_b32 m0, s58
	ds_read_b128 v[186:189], v161 offset:16384
	ds_read_b128 v[190:193], v161 offset:17408
	ds_read_b128 v[194:197], v161 offset:18432
	ds_read_b128 v[198:201], v161 offset:19456
	ds_read_b128 v[202:205], v161 offset:20480
	ds_read_b128 v[206:209], v161 offset:21504
	ds_read_b128 v[210:213], v161 offset:22528
	ds_read_b128 v[214:217], v161 offset:23552
	global_load_lds_dwordx4 v[148:149], off
	s_add_i32 m0, s58, 0x2000
	v_lshl_add_u64 v[152:153], s[56:57], 0, v[140:141]
	s_add_u32 s56, s56, s10
	s_addc_u32 s57, s57, s11
	s_add_i32 s58, s59, s35
	global_load_lds_dwordx4 v[152:153], off
	v_lshl_add_u64 v[218:219], s[56:57], 0, v[136:137]
	s_mov_b32 m0, s58
	v_lshl_add_u64 v[228:229], s[56:57], 0, v[140:141]
	global_load_lds_dwordx4 v[218:219], off
	s_add_i32 m0, s58, 0x2000
	v_lshl_add_u64 v[242:243], s[26:27], 0, v[134:135]
	global_load_lds_dwordx4 v[228:229], off
	s_mov_b32 m0, s40
	v_lshl_add_u64 v[244:245], s[26:27], 0, v[138:139]
	global_load_lds_dwordx4 v[242:243], off
	s_mov_b32 m0, s41
	s_nop 0
	global_load_lds_dwordx4 v[244:245], off
	s_cmp_eq_u32 s55, 2
	s_cbranch_scc1 .Lmy_kf2b

; #define PG8_STAGE(bufoff, gbase, voff) do { _Pragma("unroll") for (int _i = 0; _i < 2; ++_i) \
;         __builtin_amdgcn_global_load_lds((const unsigned*)((const char*)(gbase) + (voff)[_i]), (PG8_LAS unsigned*)(lds + (bufoff) + ldsw + _i * 8192), 16, 0, 0); } while (0)
; #define PG8_LDA(dst, b, h) do { _Pragma("unroll") for (int m = 0; m < 4; ++m) _Pragma("unroll") for (int k = 0; k < 2; ++k) dst[m][k] = *(const PG8_LAS bf16x8*)(lds + PG8_SA(b, h) + aoff + m * 2048 + k * 1024); } while (0)
; #define PG8_LDB(dst, b, h) do { _Pragma("unroll") for (int n = 0; n < 2; ++n) _Pragma("unroll") for (int k = 0; k < 2; ++k) dst[n][k] = *(const PG8_LAS bf16x8*)(lds + PG8_SB(b, h) + boff + n * 2048 + k * 1024); } while (0)
; #define PG8_MMA(ai, bj, At, Bt) do { __builtin_amdgcn_s_setprio(1); _Pragma("unroll") for (int m = 0; m < 4; ++m) _Pragma("unroll") for (int n = 0; n < 2; ++n) _Pragma("unroll") for (int k = 0; k < 2; ++k) \
;         acc[ai][bj][m][n] = __builtin_amdgcn_mfma_f32_16x16x32_bf16(Bt[n][k], At[m][k], acc[ai][bj][m][n], 0, 0, 0); __builtin_amdgcn_s_setprio(0); } while (0)
; #define PG8_WAIT_V(n) asm volatile("s_waitcnt vmcnt(" #n ")" ::: "memory")
; #define PG8_WAIT_L(n) asm volatile("s_waitcnt lgkmcnt(" #n ")" ::: "memory")
; #define PG8_BAR __builtin_amdgcn_s_barrier()
; #define PG8_SCHED __builtin_amdgcn_sched_barrier(0)
; template <class Epi, class Sched, bool ALIGN_EPI = false, bool SP2 = false>
; __device__ __forceinline__ void gemm_phase(PG8_LAS unsigned char* lds, const Gemm g, const Sched& S, const Epi& E) {
;     ...
;             PG8_WAIT_V(8); PG8_WAIT_L(0); PG8_BAR; PG8_MMA(1, 0, At, B0); PG8_MMA(1, 1, At, B1); PG8_BAR; PG8_SCHED;
;             PG8_LDB(B0, 1, 0); PG8_LDB(B1, 1, 1); PG8_SCHED; PG8_LDA(At, 1, 0); PG8_STAGE(PG8_SA(0, 1), a2 + hstep, voffA);
;             PG8_WAIT_V(8); PG8_WAIT_L(0); PG8_BAR; PG8_MMA(0, 0, At, B0); PG8_MMA(0, 1, At, B1); PG8_BAR; PG8_SCHED;
.Lmy_kc2b:
	s_waitcnt lgkmcnt(0)
	s_barrier
	s_setprio 1
	s_waitcnt lgkmcnt(0)
	v_mfma_f32_16x16x32_bf16 v[62:65], v[130:133], v[186:189], v[62:65]
	v_mfma_f32_16x16x32_bf16 v[58:61], v[162:165], v[186:189], v[58:61]
	v_mfma_f32_16x16x32_bf16 v[46:49], v[130:133], v[194:197], v[46:49]
	v_mfma_f32_16x16x32_bf16 v[42:45], v[162:165], v[194:197], v[42:45]
	v_mfma_f32_16x16x32_bf16 v[30:33], v[130:133], v[202:205], v[30:33]
	v_mfma_f32_16x16x32_bf16 v[26:29], v[162:165], v[202:205], v[26:29]
	v_mfma_f32_16x16x32_bf16 v[14:17], v[130:133], v[210:213], v[14:17]
	v_mfma_f32_16x16x32_bf16 v[10:13], v[162:165], v[210:213], v[10:13]
	v_mfma_f32_16x16x32_bf16 v[62:65], v[156:159], v[190:193], v[62:65]
	v_mfma_f32_16x16x32_bf16 v[58:61], v[166:169], v[190:193], v[58:61]
	v_mfma_f32_16x16x32_bf16 v[46:49], v[156:159], v[198:201], v[46:49]
	v_mfma_f32_16x16x32_bf16 v[42:45], v[166:169], v[198:201], v[42:45]
	v_mfma_f32_16x16x32_bf16 v[30:33], v[156:159], v[206:209], v[30:33]
	v_mfma_f32_16x16x32_bf16 v[26:29], v[166:169], v[206:209], v[26:29]
	v_mfma_f32_16x16x32_bf16 v[14:17], v[156:159], v[214:217], v[14:17]
	v_mfma_f32_16x16x32_bf16 v[10:13], v[166:169], v[214:217], v[10:13]
	s_setprio 0
	s_setprio 1
	v_mfma_f32_16x16x32_bf16 v[54:57], v[170:173], v[186:189], v[54:57]
	v_mfma_f32_16x16x32_bf16 v[50:53], v[178:181], v[186:189], v[50:53]
	v_mfma_f32_16x16x32_bf16 v[38:41], v[170:173], v[194:197], v[38:41]
	v_mfma_f32_16x16x32_bf16 v[34:37], v[178:181], v[194:197], v[34:37]
	v_mfma_f32_16x16x32_bf16 v[22:25], v[170:173], v[202:205], v[22:25]
	v_mfma_f32_16x16x32_bf16 v[18:21], v[178:181], v[202:205], v[18:21]
	v_mfma_f32_16x16x32_bf16 v[6:9], v[170:173], v[210:213], v[6:9]
	v_mfma_f32_16x16x32_bf16 v[2:5], v[178:181], v[210:213], v[2:5]
	v_mfma_f32_16x16x32_bf16 v[54:57], v[174:177], v[190:193], v[54:57]
	v_mfma_f32_16x16x32_bf16 v[50:53], v[182:185], v[190:193], v[50:53]
	v_mfma_f32_16x16x32_bf16 v[38:41], v[174:177], v[198:201], v[38:41]
	v_mfma_f32_16x16x32_bf16 v[34:37], v[182:185], v[198:201], v[34:37]
	v_mfma_f32_16x16x32_bf16 v[22:25], v[174:177], v[206:209], v[22:25]
	v_mfma_f32_16x16x32_bf16 v[18:21], v[182:185], v[206:209], v[18:21]
	v_mfma_f32_16x16x32_bf16 v[6:9], v[174:177], v[214:217], v[6:9]
	v_mfma_f32_16x16x32_bf16 v[2:5], v[182:185], v[214:217], v[2:5]
	s_setprio 0
	s_barrier
	s_add_i32 s56, 0, 0x18000
	v_add_u32_e32 v150, s56, v151
	s_add_i32 s57, 0, 0x1c000
	ds_read_b128 v[130:133], v150
	ds_read_b128 v[156:159], v150 offset:1024
	ds_read_b128 v[162:165], v150 offset:2048
	ds_read_b128 v[166:169], v150 offset:3072
	v_add_u32_e32 v150, s57, v151
	ds_read_b128 v[170:173], v150
	ds_read_b128 v[174:177], v150 offset:1024
	ds_read_b128 v[178:181], v150 offset:2048
	ds_read_b128 v[182:185], v150 offset:3072
	s_add_u32 s26, s26, s10
	s_addc_u32 s27, s27, s11
	s_mov_b32 m0, s42
	v_lshl_add_u64 v[246:247], s[26:27], 0, v[134:135]
	ds_read_b128 v[186:189], v161 offset:32768
	ds_read_b128 v[190:193], v161 offset:33792
	ds_read_b128 v[194:197], v161 offset:34816
	ds_read_b128 v[198:201], v161 offset:35840
	ds_read_b128 v[202:205], v161 offset:36864
	ds_read_b128 v[206:209], v161 offset:37888
	ds_read_b128 v[210:213], v161 offset:38912
	ds_read_b128 v[214:217], v161 offset:39936
	global_load_lds_dwordx4 v[246:247], off
	v_lshl_add_u64 v[246:247], s[26:27], 0, v[138:139]
	s_mov_b32 m0, s43
	s_nop 0
	global_load_lds_dwordx4 v[246:247], off
	s_waitcnt vmcnt(8)
	s_waitcnt lgkmcnt(0)
	s_barrier
	s_setprio 1
	s_waitcnt lgkmcnt(0)
	v_mfma_f32_16x16x32_bf16 v[122:125], v[130:133], v[186:189], v[122:125]
	v_mfma_f32_16x16x32_bf16 v[126:129], v[162:165], v[186:189], v[126:129]
	v_mfma_f32_16x16x32_bf16 v[110:113], v[130:133], v[194:197], v[110:113]
	v_mfma_f32_16x16x32_bf16 v[106:109], v[162:165], v[194:197], v[106:109]
	v_mfma_f32_16x16x32_bf16 v[94:97], v[130:133], v[202:205], v[94:97]
	v_mfma_f32_16x16x32_bf16 v[90:93], v[162:165], v[202:205], v[90:93]
	v_mfma_f32_16x16x32_bf16 v[78:81], v[130:133], v[210:213], v[78:81]
	v_mfma_f32_16x16x32_bf16 v[74:77], v[162:165], v[210:213], v[74:77]
	v_mfma_f32_16x16x32_bf16 v[122:125], v[156:159], v[190:193], v[122:125]
	v_mfma_f32_16x16x32_bf16 v[126:129], v[166:169], v[190:193], v[126:129]
	v_mfma_f32_16x16x32_bf16 v[110:113], v[156:159], v[198:201], v[110:113]
	v_mfma_f32_16x16x32_bf16 v[106:109], v[166:169], v[198:201], v[106:109]
	v_mfma_f32_16x16x32_bf16 v[94:97], v[156:159], v[206:209], v[94:97]
	v_mfma_f32_16x16x32_bf16 v[90:93], v[166:169], v[206:209], v[90:93]
	v_mfma_f32_16x16x32_bf16 v[78:81], v[156:159], v[214:217], v[78:81]
	v_mfma_f32_16x16x32_bf16 v[74:77], v[166:169], v[214:217], v[74:77]
	s_setprio 0
	s_setprio 1
	v_mfma_f32_16x16x32_bf16 v[118:121], v[170:173], v[186:189], v[118:121]
	v_mfma_f32_16x16x32_bf16 v[114:117], v[178:181], v[186:189], v[114:117]
	v_mfma_f32_16x16x32_bf16 v[102:105], v[170:173], v[194:197], v[102:105]
	v_mfma_f32_16x16x32_bf16 v[98:101], v[178:181], v[194:197], v[98:101]
	v_mfma_f32_16x16x32_bf16 v[86:89], v[170:173], v[202:205], v[86:89]
	v_mfma_f32_16x16x32_bf16 v[82:85], v[178:181], v[202:205], v[82:85]
	v_mfma_f32_16x16x32_bf16 v[70:73], v[170:173], v[210:213], v[70:73]
	v_mfma_f32_16x16x32_bf16 v[66:69], v[178:181], v[210:213], v[66:69]
	v_mfma_f32_16x16x32_bf16 v[118:121], v[174:177], v[190:193], v[118:121]
	v_mfma_f32_16x16x32_bf16 v[114:117], v[182:185], v[190:193], v[114:117]
	v_mfma_f32_16x16x32_bf16 v[102:105], v[174:177], v[198:201], v[102:105]
	v_mfma_f32_16x16x32_bf16 v[98:101], v[182:185], v[198:201], v[98:101]
	v_mfma_f32_16x16x32_bf16 v[86:89], v[174:177], v[206:209], v[86:89]
	v_mfma_f32_16x16x32_bf16 v[82:85], v[182:185], v[206:209], v[82:85]
	v_mfma_f32_16x16x32_bf16 v[70:73], v[174:177], v[214:217], v[70:73]
	v_mfma_f32_16x16x32_bf16 v[66:69], v[182:185], v[214:217], v[66:69]
	s_setprio 0
	s_barrier
; #define PG8_STAGE(bufoff, gbase, voff) do { _Pragma("unroll") for (int _i = 0; _i < 2; ++_i) \
;         __builtin_amdgcn_global_load_lds((const unsigned*)((const char*)(gbase) + (voff)[_i]), (PG8_LAS unsigned*)(lds + (bufoff) + ldsw + _i * 8192), 16, 0, 0); } while (0)
; #define PG8_LDA(dst, b, h) do { _Pragma("unroll") for (int m = 0; m < 4; ++m) _Pragma("unroll") for (int k = 0; k < 2; ++k) dst[m][k] = *(const PG8_LAS bf16x8*)(lds + PG8_SA(b, h) + aoff + m * 2048 + k * 1024); } while (0)
; #define PG8_MMA(ai, bj, At, Bt) do { __builtin_amdgcn_s_setprio(1); _Pragma("unroll") for (int m = 0; m < 4; ++m) _Pragma("unroll") for (int n = 0; n < 2; ++n) _Pragma("unroll") for (int k = 0; k < 2; ++k) \
;         acc[ai][bj][m][n] = __builtin_amdgcn_mfma_f32_16x16x32_bf16(Bt[n][k], At[m][k], acc[ai][bj][m][n], 0, 0, 0); __builtin_amdgcn_s_setprio(0); } while (0)
; #define PG8_WAIT_V(n) asm volatile("s_waitcnt vmcnt(" #n ")" ::: "memory")
; #define PG8_WAIT_L(n) asm volatile("s_waitcnt lgkmcnt(" #n ")" ::: "memory")
; #define PG8_BAR __builtin_amdgcn_s_barrier()
; #define PG8_SCHED __builtin_amdgcn_sched_barrier(0)
; template <class Epi, class Sched, bool ALIGN_EPI = false, bool SP2 = false>
; __device__ __forceinline__ void gemm_phase(PG8_LAS unsigned char* lds, const Gemm g, const Sched& S, const Epi& E) {
;     ...
;             PG8_WAIT_V(8); PG8_WAIT_L(0); PG8_BAR; PG8_MMA(0, 0, At, B0); PG8_MMA(0, 1, At, B1); PG8_BAR; PG8_SCHED;
;             PG8_LDA(At, 1, 1); PG8_STAGE(PG8_SB(1, 0), b3, voffB); PG8_STAGE(PG8_SB(1, 1), b3 + hstep, voffB); PG8_STAGE(PG8_SA(1, 0), a3, voffA);
;             PG8_WAIT_V(8); PG8_WAIT_L(0); PG8_BAR; PG8_MMA(1, 0, At, B0); PG8_MMA(1, 1, At, B1); PG8_BAR; PG8_SCHED;
	s_add_i32 s26, s56, s35
	v_lshl_add_u64 v[148:149], v[148:149], 0, s[92:93]
	s_mov_b32 m0, s26
	ds_read_b128 v[186:189], v161 offset:49152
	ds_read_b128 v[190:193], v161 offset:50176
	ds_read_b128 v[194:197], v161 offset:51200
	ds_read_b128 v[198:201], v161 offset:52224
	ds_read_b128 v[202:205], v161 offset:53248
	ds_read_b128 v[206:209], v161 offset:54272
	ds_read_b128 v[210:213], v161 offset:55296
	ds_read_b128 v[214:217], v161 offset:56320
	global_load_lds_dwordx4 v[148:149], off
	v_lshl_add_u64 v[148:149], v[152:153], 0, s[92:93]
	s_add_i32 m0, s26, 0x2000
	s_add_i32 s26, s57, s35
	global_load_lds_dwordx4 v[148:149], off
	v_lshl_add_u64 v[148:149], v[218:219], 0, s[92:93]
	s_mov_b32 m0, s26
	s_nop 0
	global_load_lds_dwordx4 v[148:149], off
	v_lshl_add_u64 v[148:149], v[228:229], 0, s[92:93]
	s_add_i32 m0, s26, 0x2000
	s_nop 0
	global_load_lds_dwordx4 v[148:149], off
	v_lshl_add_u64 v[148:149], v[242:243], 0, s[92:93]
	s_mov_b32 m0, s44
	s_nop 0
	global_load_lds_dwordx4 v[148:149], off
	v_lshl_add_u64 v[148:149], v[244:245], 0, s[92:93]
	s_mov_b32 m0, s45
	s_nop 0
	global_load_lds_dwordx4 v[148:149], off
	s_waitcnt vmcnt(8)
	s_waitcnt lgkmcnt(0)
	s_barrier
	s_setprio 1
	s_waitcnt lgkmcnt(0)
	v_mfma_f32_16x16x32_bf16 v[62:65], v[130:133], v[186:189], v[62:65]
	v_mfma_f32_16x16x32_bf16 v[58:61], v[162:165], v[186:189], v[58:61]
	v_mfma_f32_16x16x32_bf16 v[46:49], v[130:133], v[194:197], v[46:49]
	v_mfma_f32_16x16x32_bf16 v[42:45], v[162:165], v[194:197], v[42:45]
	v_mfma_f32_16x16x32_bf16 v[30:33], v[130:133], v[202:205], v[30:33]
	v_mfma_f32_16x16x32_bf16 v[26:29], v[162:165], v[202:205], v[26:29]
	v_mfma_f32_16x16x32_bf16 v[14:17], v[130:133], v[210:213], v[14:17]
	v_mfma_f32_16x16x32_bf16 v[10:13], v[162:165], v[210:213], v[10:13]
	v_mfma_f32_16x16x32_bf16 v[62:65], v[156:159], v[190:193], v[62:65]
	v_mfma_f32_16x16x32_bf16 v[58:61], v[166:169], v[190:193], v[58:61]
	v_mfma_f32_16x16x32_bf16 v[46:49], v[156:159], v[198:201], v[46:49]
	v_mfma_f32_16x16x32_bf16 v[42:45], v[166:169], v[198:201], v[42:45]
	v_mfma_f32_16x16x32_bf16 v[30:33], v[156:159], v[206:209], v[30:33]
	v_mfma_f32_16x16x32_bf16 v[26:29], v[166:169], v[206:209], v[26:29]
	v_mfma_f32_16x16x32_bf16 v[14:17], v[156:159], v[214:217], v[14:17]
	v_mfma_f32_16x16x32_bf16 v[10:13], v[166:169], v[214:217], v[10:13]
	s_setprio 0
	s_setprio 1
	v_mfma_f32_16x16x32_bf16 v[54:57], v[170:173], v[186:189], v[54:57]
	v_mfma_f32_16x16x32_bf16 v[50:53], v[178:181], v[186:189], v[50:53]
	v_mfma_f32_16x16x32_bf16 v[38:41], v[170:173], v[194:197], v[38:41]
	v_mfma_f32_16x16x32_bf16 v[34:37], v[178:181], v[194:197], v[34:37]
	v_mfma_f32_16x16x32_bf16 v[22:25], v[170:173], v[202:205], v[22:25]
	v_mfma_f32_16x16x32_bf16 v[18:21], v[178:181], v[202:205], v[18:21]
	v_mfma_f32_16x16x32_bf16 v[6:9], v[170:173], v[210:213], v[6:9]
	v_mfma_f32_16x16x32_bf16 v[2:5], v[178:181], v[210:213], v[2:5]
	v_mfma_f32_16x16x32_bf16 v[54:57], v[174:177], v[190:193], v[54:57]
	v_mfma_f32_16x16x32_bf16 v[50:53], v[182:185], v[190:193], v[50:53]
	v_mfma_f32_16x16x32_bf16 v[38:41], v[174:177], v[198:201], v[38:41]
	v_mfma_f32_16x16x32_bf16 v[34:37], v[182:185], v[198:201], v[34:37]
	v_mfma_f32_16x16x32_bf16 v[22:25], v[174:177], v[206:209], v[22:25]
	v_mfma_f32_16x16x32_bf16 v[18:21], v[182:185], v[206:209], v[18:21]
	v_mfma_f32_16x16x32_bf16 v[6:9], v[174:177], v[214:217], v[6:9]
	v_mfma_f32_16x16x32_bf16 v[2:5], v[182:185], v[214:217], v[2:5]
	s_setprio 0
	s_barrier
	s_add_u32 s53, s53, 0x100
	s_addc_u32 s54, s54, 0
	s_add_u32 s24, s24, 0x100
	s_addc_u32 s25, s25, 0
	s_cmp_ge_i32 s55, s46
	s_mov_b32 s26, s55
	s_cbranch_scc0 .LBB0_4845

; #define PG8_MMA(ai, bj, At, Bt) do { __builtin_amdgcn_s_setprio(1); _Pragma("unroll") for (int m = 0; m < 4; ++m) _Pragma("unroll") for (int n = 0; n < 2; ++n) _Pragma("unroll") for (int k = 0; k < 2; ++k) \
;         acc[ai][bj][m][n] = __builtin_amdgcn_mfma_f32_16x16x32_bf16(Bt[n][k], At[m][k], acc[ai][bj][m][n], 0, 0, 0); __builtin_amdgcn_s_setprio(0); } while (0)
; #define PG8_WAIT_V(n) asm volatile("s_waitcnt vmcnt(" #n ")" ::: "memory")
; #define PG8_WAIT_L(n) asm volatile("s_waitcnt lgkmcnt(" #n ")" ::: "memory")
; #define PG8_BAR __builtin_amdgcn_s_barrier()
; #define PG8_SCHED __builtin_amdgcn_sched_barrier(0)
; template <class Epi, class Sched, bool ALIGN_EPI = false, bool SP2 = false>
; __device__ __forceinline__ void gemm_phase(PG8_LAS unsigned char* lds, const Gemm g, const Sched& S, const Epi& E) {
;     ...
;             PG8_WAIT_V(8); PG8_WAIT_L(0); PG8_BAR; PG8_MMA(0, 0, At, B0); PG8_MMA(0, 1, At, B1); PG8_BAR; PG8_SCHED;
.Lmy_kf2a:
	s_cmp_gt_u32 s48, 1
	s_cbranch_scc1 .Lmy_kc2a
	s_branch .Lmy_kw2a
